# attention<true> also without a slow path: key tiles 1/3/4 skipped by a scalar test when outside the sequence, tile-4 window test folded into loop-invariant key offsets
# speedup vs baseline: 1.0005x; 1.0005x over previous
; #define LAS __attribute__((address_space(3)))
; __device__ __forceinline__ unsigned pk2(float lo, float hi) { f32x2_t v = {lo, hi}; bf16x2_t b = __builtin_convertvector(v, bf16x2_t); return __builtin_bit_cast(unsigned, b); }
; template <bool FUSED> __device__ __forceinline__ void attn_phase(const Args& a, LAS unsigned char* lds, int tid, int lane, int wave) {
;     ...
;         const float bsl = __builtin_amdgcn_exp2f(-(float)(slot + 1)) * (float)w.dil * LOG2E;
;         int tl = 4 * h - l31; asm volatile("" : "+v"(tl));
;         const float tlf = (float)tl;
;         const int lo_i = -iq > -64 ? -iq : -64, hi_i = (L - 1 - iq) < 64 ? (L - 1 - iq) : 64;
;         const float rlo = (float)lo_i, rhi = (float)hi_i;
;         const int wq0 = i0 + 32 * wave;
;         const bool edge = (wq0 < 64) || (wq0 + 32 > L - 64);
;         float sum = 0.f;
;         f32x16 o[2]; o[0] = f32x16{}; o[1] = f32x16{};
; #pragma unroll
;         for (int j = 0; j < 5; ++j) {
;             f32x16 st;
; #pragma unroll
;             for (int i = 0; i < 16; ++i) st[i] = -mb;
;             LAS const unsigned char* kp = lds + (32 * wave + 32 * j + l31) * KP + 16 * h;
; #pragma unroll
;             for (int ks = 0; ks < 4; ++ks) { const bf16x8 kf = *(LAS const bf16x8*)(kp + 32 * ks); st = __builtin_amdgcn_mfma_f32_32x32x16_bf16(kf, qf[ks], st, 0, 0, 0); }
;             sum += attn_tile_exp(st, j, tlf, bsl, rlo, rhi);
; #pragma unroll
;             for (int s2 = 0; s2 < 2; ++s2) { u32x4 pw; pw.x = pk2(st[8 * s2 + 0], st[8 * s2 + 1]); pw.y = pk2(st[8 * s2 + 2], st[8 * s2 + 3]); pw.z = pk2(st[8 * s2 + 4], st[8 * s2 + 5]); pw.w = pk2(st[8 * s2 + 6], st[8 * s2 + 7]);
;                 const bf16x8 pf = __builtin_bit_cast(bf16x8, pw);
;                 LAS const unsigned char* vp = lds + LDS_VOFF + (32 * wave + 32 * j + 16 * s2 + 4 * h + q) * VP + 32 * blk + 8 * p;
; #pragma unroll
;                 for (int dt = 0; dt < 2; ++dt) { const s16x4 lo = trrd(vp + dt * 64), hi = trrd(vp + 8 * VP + dt * 64);
;                     const bf16x8 vf = __builtin_shufflevector(lo, hi, 0, 1, 2, 3, 4, 5, 6, 7);
;                     o[dt] = __builtin_amdgcn_mfma_f32_32x32x16_bf16(vf, pf, o[dt], 0, 0, 0); } }
;             __builtin_amdgcn_sched_barrier(0);
;         }
.Lattn2_join:
	v_xor_b32_e32 v32, 0x80000000, v229
	v_mov_b32_e32 v33, v32
	v_mov_b32_e32 v34, v32
	v_mov_b32_e32 v35, v32
	v_mov_b32_e32 v36, v32
	v_mov_b32_e32 v37, v32
	v_mov_b32_e32 v38, v32
	v_mov_b32_e32 v39, v32
	v_mov_b32_e32 v40, v32
	v_mov_b32_e32 v41, v32
	v_mov_b32_e32 v42, v32
	v_mov_b32_e32 v43, v32
	v_mov_b32_e32 v44, v32
	v_mov_b32_e32 v45, v32
	v_mov_b32_e32 v46, v32
	v_mov_b32_e32 v47, v32
	s_and_b32 s8, s8, 31
	s_waitcnt lgkmcnt(0)
	v_mfma_f32_32x32x16_bf16 v[0:15], v[20:23], v[96:99], v[32:47]
	ds_read_b128 v[20:23], v206 offset:64
	v_cvt_f32_ubyte0_e32 v16, s6
	v_exp_f32_e64 v29, -v16
	v_mfma_f32_32x32x16_bf16 v[0:15], v[24:27], v[100:103], v[0:15]
	s_lshl_b32 s66, s8, 8
	ds_read_b128 v[16:19], v206 offset:96
	s_add_i32 s66, s66, s48
	s_lshl_b32 s9, 1, s7
	s_lshr_b32 s7, 0x2000, s7
	s_waitcnt lgkmcnt(1)
	v_mfma_f32_32x32x16_bf16 v[0:15], v[20:23], v[104:107], v[0:15]
	v_or_b32_e32 v62, s66, v145
	v_sub_u32_e32 v20, 0, v62
	v_xad_u32 v21, v62, -1, s7
	v_cvt_f32_u32_e32 v24, s9
	v_cvt_f32_i32_e32 v171, v28
	v_max_i32_e32 v20, 0xffffffc0, v20
	v_min_i32_e32 v21, 64, v21
	s_waitcnt lgkmcnt(0)
	v_mfma_f32_32x32x16_bf16 v[0:15], v[16:19], v[108:111], v[0:15]
	v_readfirstlane_b32 s98, v62
	s_sub_i32 s99, s7, 64
	v_cvt_f32_i32_e32 v168, v20
	v_cvt_f32_i32_e32 v169, v21
	v_mul_f32_e32 v24, v29, v24
	v_add_f32_e32 v16, 0xc2800000, v171
	v_mul_f32_e32 v170, 0xbfb8aa3b, v24
	v_cmp_nge_f32_e32 vcc, v16, v168
	v_cmp_nle_f32_e64 s[6:7], v16, v169
	s_nop 4
	v_fma_f32 v0, v170, |v16|, v0
	s_or_b64 vcc, vcc, s[6:7]
	v_add_f32_e32 v17, 0xc27c0000, v171
	v_cndmask_b32_e32 v0, v0, v228, vcc
	v_cmp_nge_f32_e32 vcc, v17, v168
	v_cmp_nle_f32_e64 s[6:7], v17, v169
	v_fma_f32 v1, v170, |v17|, v1
	s_or_b64 vcc, vcc, s[6:7]
	v_cndmask_b32_e32 v1, v1, v228, vcc
	v_exp_f32_e32 v17, v1
	v_add_f32_e32 v1, 0xc2780000, v171
	v_cmp_nge_f32_e32 vcc, v1, v168
	v_cmp_nle_f32_e64 s[6:7], v1, v169
	v_fma_f32 v2, v170, |v1|, v2
	s_or_b64 vcc, vcc, s[6:7]
	v_cndmask_b32_e32 v1, v2, v228, vcc
	v_exp_f32_e32 v18, v1
	v_add_f32_e32 v1, 0xc2740000, v171
	v_cmp_nge_f32_e32 vcc, v1, v168
	v_cmp_nle_f32_e64 s[6:7], v1, v169
	v_fma_f32 v2, v170, |v1|, v3
	s_or_b64 vcc, vcc, s[6:7]
	v_cndmask_b32_e32 v1, v2, v228, vcc
	v_exp_f32_e32 v19, v1
	v_add_f32_e32 v1, 0xc2600000, v171
	v_cmp_nge_f32_e32 vcc, v1, v168
	v_cmp_nle_f32_e64 s[6:7], v1, v169
	v_fma_f32 v2, v170, |v1|, v4
	s_or_b64 vcc, vcc, s[6:7]
	v_cndmask_b32_e32 v1, v2, v228, vcc
	v_exp_f32_e32 v20, v1
	v_add_f32_e32 v1, 0xc25c0000, v171
	v_cmp_nge_f32_e32 vcc, v1, v168
	v_cmp_nle_f32_e64 s[6:7], v1, v169
	v_fma_f32 v2, v170, |v1|, v5
	s_or_b64 vcc, vcc, s[6:7]
	v_cndmask_b32_e32 v1, v2, v228, vcc
	v_exp_f32_e32 v21, v1
	v_add_f32_e32 v1, 0xc2580000, v171
	v_cmp_nge_f32_e32 vcc, v1, v168
	v_cmp_nle_f32_e64 s[6:7], v1, v169
	v_fma_f32 v2, v170, |v1|, v6
	s_or_b64 vcc, vcc, s[6:7]
	v_cndmask_b32_e32 v1, v2, v228, vcc
	v_exp_f32_e32 v16, v0
	v_exp_f32_e32 v22, v1
	v_add_f32_e32 v1, 0xc2540000, v171
	v_cmp_nge_f32_e32 vcc, v1, v168
	v_cmp_nle_f32_e64 s[6:7], v1, v169
	v_fma_f32 v2, v170, |v1|, v7
	s_or_b64 vcc, vcc, s[6:7]
	v_cndmask_b32_e32 v1, v2, v228, vcc
	v_add_f32_e32 v0, 0, v16
	v_exp_f32_e32 v7, v1
	v_add_f32_e32 v1, 0xc2400000, v171
	v_add_f32_e32 v0, v17, v0
	v_cmp_nge_f32_e32 vcc, v1, v168
	v_cmp_nle_f32_e64 s[6:7], v1, v169
	v_add_f32_e32 v0, v18, v0
	v_fma_f32 v2, v170, |v1|, v8
	s_or_b64 vcc, vcc, s[6:7]
	v_add_f32_e32 v0, v19, v0
	v_cndmask_b32_e32 v1, v2, v228, vcc
	v_add_f32_e32 v0, v20, v0
	v_exp_f32_e32 v52, v1
	v_add_f32_e32 v0, v21, v0
	v_add_f32_e32 v0, v22, v0
	v_add_f32_e32 v0, v7, v0
	v_add_f32_e32 v60, v52, v0
	v_add_f32_e32 v0, 0xc23c0000, v171
	v_cmp_nge_f32_e32 vcc, v0, v168
	v_cmp_nle_f32_e64 s[6:7], v0, v169
	v_fma_f32 v1, v170, |v0|, v9
	s_or_b64 vcc, vcc, s[6:7]
	v_cndmask_b32_e32 v0, v1, v228, vcc
	v_exp_f32_e32 v61, v0
	v_add_f32_e32 v0, 0xc2380000, v171
	v_cmp_nge_f32_e32 vcc, v0, v168
	v_cmp_nle_f32_e64 s[6:7], v0, v169
	v_fma_f32 v1, v170, |v0|, v10
	s_or_b64 vcc, vcc, s[6:7]
	v_cndmask_b32_e32 v0, v1, v228, vcc
	v_exp_f32_e32 v62, v0
	v_add_f32_e32 v0, 0xc2340000, v171
	v_cmp_nge_f32_e32 vcc, v0, v168
	v_cmp_nle_f32_e64 s[6:7], v0, v169
	v_fma_f32 v1, v170, |v0|, v11
	s_or_b64 vcc, vcc, s[6:7]
	v_cndmask_b32_e32 v0, v1, v228, vcc
	v_exp_f32_e32 v63, v0
	v_add_f32_e32 v0, 0xc2200000, v171
	v_cmp_nge_f32_e32 vcc, v0, v168
	v_cmp_nle_f32_e64 s[6:7], v0, v169
	v_fma_f32 v1, v170, |v0|, v12
	s_or_b64 vcc, vcc, s[6:7]
	v_cndmask_b32_e32 v0, v1, v228, vcc
	v_exp_f32_e32 v172, v0
	v_add_f32_e32 v0, 0xc21c0000, v171
	v_cmp_nge_f32_e32 vcc, v0, v168
	v_cmp_nle_f32_e64 s[6:7], v0, v169
	v_fma_f32 v1, v170, |v0|, v13
	s_or_b64 vcc, vcc, s[6:7]
	v_cndmask_b32_e32 v0, v1, v228, vcc
	v_exp_f32_e32 v173, v0
	v_add_f32_e32 v0, 0xc2180000, v171
	v_cmp_nge_f32_e32 vcc, v0, v168
	v_cmp_nle_f32_e64 s[6:7], v0, v169
	v_fma_f32 v1, v170, |v0|, v14
	s_or_b64 vcc, vcc, s[6:7]
	v_cndmask_b32_e32 v4, v1, v228, vcc
	ds_read_b64_tr_b16 v[0:1], v207 offset:55296
	ds_read_b64_tr_b16 v[2:3], v207 offset:56832
	ds_read_b64_tr_b16 v[10:11], v207 offset:56896
	ds_read_b64_tr_b16 v[8:9], v207 offset:55360
	v_add_f32_e32 v12, 0xc2140000, v171
	v_exp_f32_e32 v174, v4
	v_cvt_pk_bf16_f32 v4, v16, v17
	v_cvt_pk_bf16_f32 v5, v18, v19
	v_cvt_pk_bf16_f32 v6, v20, v21
	v_cvt_pk_bf16_f32 v7, v22, v7
	v_cmp_nge_f32_e32 vcc, v12, v168
	v_cmp_nle_f32_e64 s[6:7], v12, v169
	s_waitcnt lgkmcnt(2)
	v_mfma_f32_32x32x16_bf16 v[16:31], v[0:3], v[4:7], 0
	v_fma_f32 v0, v170, |v12|, v15
	s_or_b64 vcc, vcc, s[6:7]
	v_cndmask_b32_e32 v53, v0, v228, vcc
	ds_read_b64_tr_b16 v[48:49], v207 offset:58368
	ds_read_b64_tr_b16 v[50:51], v207 offset:59904
	v_exp_f32_e32 v175, v53
	ds_read_b64_tr_b16 v[58:59], v207 offset:59968
	ds_read_b64_tr_b16 v[56:57], v207 offset:58432
	v_cvt_pk_bf16_f32 v52, v52, v61
	s_waitcnt lgkmcnt(4)
	v_mfma_f32_32x32x16_bf16 v[0:15], v[8:11], v[4:7], 0
	v_cvt_pk_bf16_f32 v53, v62, v63
	v_cvt_pk_bf16_f32 v54, v172, v173
	v_cvt_pk_bf16_f32 v55, v174, v175
	s_waitcnt lgkmcnt(2)
	s_nop 0
	v_mfma_f32_32x32x16_bf16 v[16:31], v[48:51], v[52:55], v[16:31]
	v_add_f32_e32 v48, v61, v60
	v_add_f32_e32 v48, v62, v48
	v_add_f32_e32 v48, v63, v48
	v_add_f32_e32 v48, v172, v48
	v_add_f32_e32 v48, v173, v48
	v_add_f32_e32 v48, v174, v48
	v_add_f32_e32 v48, v175, v48
	s_waitcnt lgkmcnt(0)
	v_mfma_f32_32x32x16_bf16 v[0:15], v[56:59], v[52:55], v[0:15]
	v_add_f32_e32 v238, 0, v48
	s_cmp_lt_i32 s98, 32
	s_cbranch_scc1 .Lattn2_skip1
; #define LAS __attribute__((address_space(3)))
; __device__ __forceinline__ unsigned pk2(float lo, float hi) { f32x2_t v = {lo, hi}; bf16x2_t b = __builtin_convertvector(v, bf16x2_t); return __builtin_bit_cast(unsigned, b); }
; __device__ __forceinline__ s16x4 trrd(LAS const unsigned char* p) { return __builtin_bit_cast(s16x4, __builtin_amdgcn_ds_read_tr16_b64_v4i16((LAS v4i16_t*)p)); }
; template <bool FUSED> __device__ __forceinline__ void attn_phase(const Args& a, LAS unsigned char* lds, int tid, int lane, int wave) {
;     ...
;         for (int j = 0; j < 5; ++j) {
;             f32x16 st;
; #pragma unroll
;             for (int i = 0; i < 16; ++i) st[i] = -mb;
;             LAS const unsigned char* kp = lds + (32 * wave + 32 * j + l31) * KP + 16 * h;
; #pragma unroll
;             for (int ks = 0; ks < 4; ++ks) { const bf16x8 kf = *(LAS const bf16x8*)(kp + 32 * ks); st = __builtin_amdgcn_mfma_f32_32x32x16_bf16(kf, qf[ks], st, 0, 0, 0); }
;             sum += attn_tile_exp(st, j, tlf, bsl, rlo, rhi);
; #pragma unroll
;             for (int s2 = 0; s2 < 2; ++s2) { u32x4 pw; pw.x = pk2(st[8 * s2 + 0], st[8 * s2 + 1]); pw.y = pk2(st[8 * s2 + 2], st[8 * s2 + 3]); pw.z = pk2(st[8 * s2 + 4], st[8 * s2 + 5]); pw.w = pk2(st[8 * s2 + 6], st[8 * s2 + 7]);
;                 const bf16x8 pf = __builtin_bit_cast(bf16x8, pw);
;                 LAS const unsigned char* vp = lds + LDS_VOFF + (32 * wave + 32 * j + 16 * s2 + 4 * h + q) * VP + 32 * blk + 8 * p;
; #pragma unroll
;                 for (int dt = 0; dt < 2; ++dt) { const s16x4 lo = trrd(vp + dt * 64), hi = trrd(vp + 8 * VP + dt * 64);
;                     const bf16x8 vf = __builtin_shufflevector(lo, hi, 0, 1, 2, 3, 4, 5, 6, 7);
;                     o[dt] = __builtin_amdgcn_mfma_f32_32x32x16_bf16(vf, pf, o[dt], 0, 0, 0); } }
;             __builtin_amdgcn_sched_barrier(0);
;         }
	ds_read_b128 v[172:175], v208
	ds_read_b128 v[230:233], v208 offset:32
	v_add_f32_e32 v239, 0xc2000000, v171
	v_add_f32_e32 v240, 0xc1f80000, v171
	s_waitcnt lgkmcnt(1)
	v_mfma_f32_32x32x16_bf16 v[48:63], v[172:175], v[96:99], v[32:47]
	ds_read_b128 v[172:175], v208 offset:64
	ds_read_b128 v[234:237], v208 offset:96
	v_add_f32_e32 v241, 0xc1f00000, v171
	v_add_f32_e32 v242, 0xc1e80000, v171
	s_waitcnt lgkmcnt(2)
	v_mfma_f32_32x32x16_bf16 v[48:63], v[230:233], v[100:103], v[48:63]
	v_add_f32_e32 v230, 0xc1c00000, v171
	v_add_f32_e32 v231, 0xc1b80000, v171
	s_waitcnt lgkmcnt(1)
	v_mfma_f32_32x32x16_bf16 v[48:63], v[172:175], v[104:107], v[48:63]
	s_waitcnt lgkmcnt(0)
	v_mfma_f32_32x32x16_bf16 v[48:63], v[234:237], v[108:111], v[48:63]
	s_nop 11
	v_fma_f32 v48, v170, |v239|, v48
	v_fma_f32 v49, v170, |v240|, v49
	v_fma_f32 v50, v170, |v241|, v50
	v_fma_f32 v51, v170, |v242|, v51
	v_fma_f32 v52, v170, |v230|, v52
	v_fma_f32 v53, v170, |v231|, v53
	v_exp_f32_e32 v173, v49
	v_mov_b32_e32 v49, v53
	v_exp_f32_e32 v231, v49
	v_add_f32_e32 v49, 0xc1b00000, v171
	v_exp_f32_e32 v174, v50
	v_fma_f32 v49, v170, |v49|, v54
	v_exp_f32_e32 v172, v48
	v_exp_f32_e32 v232, v49
	v_add_f32_e32 v49, 0xc1a80000, v171
	v_fma_f32 v49, v170, |v49|, v55
	v_exp_f32_e32 v175, v51
	v_exp_f32_e32 v230, v52
	v_add_f32_e32 v48, 0, v172
	v_exp_f32_e32 v55, v49
	v_add_f32_e32 v49, 0xc1800000, v171
	v_add_f32_e32 v48, v173, v48
	v_add_f32_e32 v48, v174, v48
	v_fma_f32 v49, v170, |v49|, v56
	v_add_f32_e32 v48, v175, v48
	v_add_f32_e32 v48, v230, v48
	v_exp_f32_e32 v233, v49
	v_add_f32_e32 v48, v231, v48
	v_add_f32_e32 v48, v232, v48
	v_add_f32_e32 v48, v55, v48
	v_add_f32_e32 v234, v233, v48
	v_add_f32_e32 v48, 0xc1700000, v171
	v_fma_f32 v48, v170, |v48|, v57
	v_exp_f32_e32 v235, v48
	v_add_f32_e32 v48, 0xc1600000, v171
	v_fma_f32 v48, v170, |v48|, v58
	v_exp_f32_e32 v236, v48
	v_add_f32_e32 v48, 0xc1500000, v171
	v_fma_f32 v48, v170, |v48|, v59
	v_exp_f32_e32 v237, v48
	v_add_f32_e32 v48, 0xc1000000, v171
	v_fma_f32 v48, v170, |v48|, v60
	v_exp_f32_e32 v60, v48
	v_add_f32_e32 v48, 0xc0e00000, v171
	v_fma_f32 v48, v170, |v48|, v61
	v_exp_f32_e32 v61, v48
	v_add_f32_e32 v48, 0xc0c00000, v171
	v_fma_f32 v52, v170, |v48|, v62
	ds_read_b64_tr_b16 v[48:49], v209 offset:55296
	ds_read_b64_tr_b16 v[50:51], v209 offset:56832
	ds_read_b64_tr_b16 v[58:59], v209 offset:56896
	ds_read_b64_tr_b16 v[56:57], v209 offset:55360
	v_exp_f32_e32 v62, v52
	v_add_f32_e32 v239, 0xc0a00000, v171
	v_cvt_pk_bf16_f32 v52, v172, v173
	v_cvt_pk_bf16_f32 v53, v174, v175
	v_cvt_pk_bf16_f32 v54, v230, v231
	v_cvt_pk_bf16_f32 v55, v232, v55
	s_waitcnt lgkmcnt(2)
	s_nop 0
	v_mfma_f32_32x32x16_bf16 v[16:31], v[48:51], v[52:55], v[16:31]
	v_fma_f32 v63, v170, |v239|, v63
	ds_read_b64_tr_b16 v[48:49], v209 offset:58368
	ds_read_b64_tr_b16 v[50:51], v209 offset:59904
	v_exp_f32_e32 v63, v63
	s_waitcnt lgkmcnt(2)
	v_mfma_f32_32x32x16_bf16 v[0:15], v[56:59], v[52:55], v[0:15]
	ds_read_b64_tr_b16 v[58:59], v209 offset:59968
	ds_read_b64_tr_b16 v[56:57], v209 offset:58432
	v_cvt_pk_bf16_f32 v52, v233, v235
	v_cvt_pk_bf16_f32 v53, v236, v237
	v_cvt_pk_bf16_f32 v54, v60, v61
	v_cvt_pk_bf16_f32 v55, v62, v63
	s_waitcnt lgkmcnt(2)
	s_nop 0
	v_mfma_f32_32x32x16_bf16 v[16:31], v[48:51], v[52:55], v[16:31]
	v_add_f32_e32 v48, v235, v234
	v_add_f32_e32 v48, v236, v48
	v_add_f32_e32 v48, v237, v48
	v_add_f32_e32 v48, v60, v48
	v_add_f32_e32 v48, v61, v48
	v_add_f32_e32 v48, v62, v48
	v_add_f32_e32 v48, v63, v48
	s_waitcnt lgkmcnt(0)
	v_mfma_f32_32x32x16_bf16 v[0:15], v[56:59], v[52:55], v[0:15]
	v_add_f32_e32 v238, v238, v48
.Lattn2_skip1:
	ds_read_b128 v[172:175], v210
	ds_read_b128 v[230:233], v210 offset:32
	v_add_f32_e32 v239, 1.0, v171
	s_waitcnt lgkmcnt(1)
	v_mfma_f32_32x32x16_bf16 v[48:63], v[172:175], v[96:99], v[32:47]
	ds_read_b128 v[172:175], v210 offset:64
	ds_read_b128 v[234:237], v210 offset:96
	s_waitcnt lgkmcnt(2)
	v_mfma_f32_32x32x16_bf16 v[48:63], v[230:233], v[100:103], v[48:63]
	v_add_f32_e32 v230, 2.0, v171
	v_add_f32_e32 v231, 0x40400000, v171
	v_add_f32_e32 v232, 0x41000000, v171
	s_waitcnt lgkmcnt(1)
	v_mfma_f32_32x32x16_bf16 v[48:63], v[172:175], v[104:107], v[48:63]
	v_add_f32_e32 v233, 0x41100000, v171
	s_waitcnt lgkmcnt(0)
	v_mfma_f32_32x32x16_bf16 v[48:63], v[234:237], v[108:111], v[48:63]
	s_nop 11
	v_fma_f32 v48, v170, |v171|, v48
	v_fma_f32 v49, v170, |v239|, v49
	v_fma_f32 v50, v170, |v230|, v50
	v_fma_f32 v51, v170, |v231|, v51
	v_fma_f32 v52, v170, |v232|, v52
	v_fma_f32 v53, v170, |v233|, v53
	v_exp_f32_e32 v173, v49
	v_mov_b32_e32 v49, v53
	v_exp_f32_e32 v231, v49
	v_add_f32_e32 v49, 0x41200000, v171
	v_exp_f32_e32 v174, v50
	v_fma_f32 v49, v170, |v49|, v54
	v_exp_f32_e32 v172, v48
	v_exp_f32_e32 v232, v49
	v_add_f32_e32 v49, 0x41300000, v171
	v_fma_f32 v49, v170, |v49|, v55
	v_exp_f32_e32 v175, v51
	v_exp_f32_e32 v230, v52
	v_add_f32_e32 v48, 0, v172
	v_exp_f32_e32 v55, v49
	v_add_f32_e32 v49, 0x41800000, v171
	v_add_f32_e32 v48, v173, v48
	v_add_f32_e32 v48, v174, v48
	v_fma_f32 v49, v170, |v49|, v56
	v_add_f32_e32 v48, v175, v48
	v_add_f32_e32 v48, v230, v48
	v_exp_f32_e32 v233, v49
	v_add_f32_e32 v48, v231, v48
	v_add_f32_e32 v48, v232, v48
	v_add_f32_e32 v48, v55, v48
	v_add_f32_e32 v234, v233, v48
	v_add_f32_e32 v48, 0x41880000, v171
	v_fma_f32 v48, v170, |v48|, v57
	v_exp_f32_e32 v235, v48
	v_add_f32_e32 v48, 0x41900000, v171
	v_fma_f32 v48, v170, |v48|, v58
	v_exp_f32_e32 v236, v48
	v_add_f32_e32 v48, 0x41980000, v171
	v_fma_f32 v48, v170, |v48|, v59
	v_exp_f32_e32 v237, v48
	v_add_f32_e32 v48, 0x41c00000, v171
	v_fma_f32 v48, v170, |v48|, v60
	v_exp_f32_e32 v60, v48
	v_add_f32_e32 v48, 0x41c80000, v171
	v_fma_f32 v48, v170, |v48|, v61
	v_exp_f32_e32 v61, v48
	v_add_f32_e32 v48, 0x41d00000, v171
	v_fma_f32 v52, v170, |v48|, v62
	ds_read_b64_tr_b16 v[48:49], v211 offset:55296
	ds_read_b64_tr_b16 v[50:51], v211 offset:56832
	ds_read_b64_tr_b16 v[58:59], v211 offset:56896
	ds_read_b64_tr_b16 v[56:57], v211 offset:55360
	v_exp_f32_e32 v62, v52
	v_add_f32_e32 v239, 0x41d80000, v171
	v_cvt_pk_bf16_f32 v52, v172, v173
	v_cvt_pk_bf16_f32 v53, v174, v175
	v_cvt_pk_bf16_f32 v54, v230, v231
	v_cvt_pk_bf16_f32 v55, v232, v55
	s_waitcnt lgkmcnt(2)
; #define LAS __attribute__((address_space(3)))
; __device__ __forceinline__ unsigned pk2(float lo, float hi) { f32x2_t v = {lo, hi}; bf16x2_t b = __builtin_convertvector(v, bf16x2_t); return __builtin_bit_cast(unsigned, b); }
; __device__ __forceinline__ s16x4 trrd(LAS const unsigned char* p) { return __builtin_bit_cast(s16x4, __builtin_amdgcn_ds_read_tr16_b64_v4i16((LAS v4i16_t*)p)); }
; template <bool FUSED> __device__ __forceinline__ void attn_phase(const Args& a, LAS unsigned char* lds, int tid, int lane, int wave) {
;     ...
;         for (int j = 0; j < 5; ++j) {
;             f32x16 st;
; #pragma unroll
;             for (int i = 0; i < 16; ++i) st[i] = -mb;
;             LAS const unsigned char* kp = lds + (32 * wave + 32 * j + l31) * KP + 16 * h;
; #pragma unroll
;             for (int ks = 0; ks < 4; ++ks) { const bf16x8 kf = *(LAS const bf16x8*)(kp + 32 * ks); st = __builtin_amdgcn_mfma_f32_32x32x16_bf16(kf, qf[ks], st, 0, 0, 0); }
;             sum += attn_tile_exp(st, j, tlf, bsl, rlo, rhi);
; #pragma unroll
;             for (int s2 = 0; s2 < 2; ++s2) { u32x4 pw; pw.x = pk2(st[8 * s2 + 0], st[8 * s2 + 1]); pw.y = pk2(st[8 * s2 + 2], st[8 * s2 + 3]); pw.z = pk2(st[8 * s2 + 4], st[8 * s2 + 5]); pw.w = pk2(st[8 * s2 + 6], st[8 * s2 + 7]);
;                 const bf16x8 pf = __builtin_bit_cast(bf16x8, pw);
;                 LAS const unsigned char* vp = lds + LDS_VOFF + (32 * wave + 32 * j + 16 * s2 + 4 * h + q) * VP + 32 * blk + 8 * p;
; #pragma unroll
;                 for (int dt = 0; dt < 2; ++dt) { const s16x4 lo = trrd(vp + dt * 64), hi = trrd(vp + 8 * VP + dt * 64);
;                     const bf16x8 vf = __builtin_shufflevector(lo, hi, 0, 1, 2, 3, 4, 5, 6, 7);
;                     o[dt] = __builtin_amdgcn_mfma_f32_32x32x16_bf16(vf, pf, o[dt], 0, 0, 0); } }
;             __builtin_amdgcn_sched_barrier(0);
;         }
	s_nop 0
	v_mfma_f32_32x32x16_bf16 v[16:31], v[48:51], v[52:55], v[16:31]
	v_fma_f32 v63, v170, |v239|, v63
	ds_read_b64_tr_b16 v[48:49], v211 offset:58368
	ds_read_b64_tr_b16 v[50:51], v211 offset:59904
	v_exp_f32_e32 v63, v63
	s_waitcnt lgkmcnt(2)
	v_mfma_f32_32x32x16_bf16 v[0:15], v[56:59], v[52:55], v[0:15]
	ds_read_b64_tr_b16 v[58:59], v211 offset:59968
	ds_read_b64_tr_b16 v[56:57], v211 offset:58432
	v_cvt_pk_bf16_f32 v52, v233, v235
	v_cvt_pk_bf16_f32 v53, v236, v237
	v_cvt_pk_bf16_f32 v54, v60, v61
	v_cvt_pk_bf16_f32 v55, v62, v63
	s_waitcnt lgkmcnt(2)
	s_nop 0
	v_mfma_f32_32x32x16_bf16 v[16:31], v[48:51], v[52:55], v[16:31]
	v_add_f32_e32 v48, v235, v234
	v_add_f32_e32 v48, v236, v48
	v_add_f32_e32 v48, v237, v48
	v_add_f32_e32 v48, v60, v48
	v_add_f32_e32 v48, v61, v48
	v_add_f32_e32 v48, v62, v48
	v_add_f32_e32 v48, v63, v48
	s_waitcnt lgkmcnt(0)
	v_mfma_f32_32x32x16_bf16 v[0:15], v[56:59], v[52:55], v[0:15]
	v_add_f32_e32 v238, v238, v48
	s_cmp_gt_i32 s98, s99
	s_cbranch_scc1 .Lattn2_skip3
	ds_read_b128 v[172:175], v212
	ds_read_b128 v[230:233], v212 offset:32
	v_add_f32_e32 v239, 0x42000000, v171
	v_add_f32_e32 v240, 0x42040000, v171
	s_waitcnt lgkmcnt(1)
	v_mfma_f32_32x32x16_bf16 v[48:63], v[172:175], v[96:99], v[32:47]
	ds_read_b128 v[172:175], v212 offset:64
	ds_read_b128 v[234:237], v212 offset:96
	v_add_f32_e32 v241, 0x42080000, v171
	v_add_f32_e32 v242, 0x420c0000, v171
	s_waitcnt lgkmcnt(2)
	v_mfma_f32_32x32x16_bf16 v[48:63], v[230:233], v[100:103], v[48:63]
	v_add_f32_e32 v230, 0x42200000, v171
	v_add_f32_e32 v231, 0x42240000, v171
	s_waitcnt lgkmcnt(1)
	v_mfma_f32_32x32x16_bf16 v[48:63], v[172:175], v[104:107], v[48:63]
	s_waitcnt lgkmcnt(0)
	v_mfma_f32_32x32x16_bf16 v[48:63], v[234:237], v[108:111], v[48:63]
	s_nop 11
	v_fma_f32 v48, v170, |v239|, v48
	v_fma_f32 v49, v170, |v240|, v49
	v_fma_f32 v50, v170, |v241|, v50
	v_fma_f32 v51, v170, |v242|, v51
	v_fma_f32 v52, v170, |v230|, v52
	v_fma_f32 v53, v170, |v231|, v53
	v_exp_f32_e32 v173, v49
	v_mov_b32_e32 v49, v53
	v_exp_f32_e32 v231, v49
	v_add_f32_e32 v49, 0x42280000, v171
	v_exp_f32_e32 v174, v50
	v_fma_f32 v49, v170, |v49|, v54
	v_exp_f32_e32 v172, v48
	v_exp_f32_e32 v232, v49
	v_add_f32_e32 v49, 0x422c0000, v171
	v_fma_f32 v49, v170, |v49|, v55
	v_exp_f32_e32 v175, v51
	v_exp_f32_e32 v230, v52
	v_add_f32_e32 v48, 0, v172
	v_exp_f32_e32 v55, v49
	v_add_f32_e32 v49, 0x42400000, v171
	v_add_f32_e32 v48, v173, v48
	v_add_f32_e32 v48, v174, v48
	v_fma_f32 v49, v170, |v49|, v56
	v_add_f32_e32 v48, v175, v48
	v_add_f32_e32 v48, v230, v48
	v_exp_f32_e32 v233, v49
	v_add_f32_e32 v48, v231, v48
	v_add_f32_e32 v48, v232, v48
	v_add_f32_e32 v48, v55, v48
	v_add_f32_e32 v234, v233, v48
	v_add_f32_e32 v48, 0x42440000, v171
	v_fma_f32 v48, v170, |v48|, v57
	v_exp_f32_e32 v235, v48
	v_add_f32_e32 v48, 0x42480000, v171
	v_fma_f32 v48, v170, |v48|, v58
	v_exp_f32_e32 v236, v48
	v_add_f32_e32 v48, 0x424c0000, v171
	v_fma_f32 v48, v170, |v48|, v59
	v_exp_f32_e32 v237, v48
	v_add_f32_e32 v48, 0x42600000, v171
	v_fma_f32 v48, v170, |v48|, v60
	v_exp_f32_e32 v60, v48
	v_add_f32_e32 v48, 0x42640000, v171
	v_fma_f32 v48, v170, |v48|, v61
	v_exp_f32_e32 v61, v48
	v_add_f32_e32 v48, 0x42680000, v171
	v_fma_f32 v52, v170, |v48|, v62
	ds_read_b64_tr_b16 v[48:49], v213 offset:55296
	ds_read_b64_tr_b16 v[50:51], v213 offset:56832
	ds_read_b64_tr_b16 v[58:59], v213 offset:56896
	ds_read_b64_tr_b16 v[56:57], v213 offset:55360
	v_exp_f32_e32 v62, v52
	v_add_f32_e32 v239, 0x426c0000, v171
	v_cvt_pk_bf16_f32 v52, v172, v173
	v_cvt_pk_bf16_f32 v53, v174, v175
	v_cvt_pk_bf16_f32 v54, v230, v231
	v_cvt_pk_bf16_f32 v55, v232, v55
	s_waitcnt lgkmcnt(2)
	s_nop 0
	v_mfma_f32_32x32x16_bf16 v[16:31], v[48:51], v[52:55], v[16:31]
	v_fma_f32 v63, v170, |v239|, v63
	ds_read_b64_tr_b16 v[48:49], v213 offset:58368
	ds_read_b64_tr_b16 v[50:51], v213 offset:59904
	v_exp_f32_e32 v63, v63
	s_waitcnt lgkmcnt(2)
	v_mfma_f32_32x32x16_bf16 v[0:15], v[56:59], v[52:55], v[0:15]
	ds_read_b64_tr_b16 v[58:59], v213 offset:59968
	ds_read_b64_tr_b16 v[56:57], v213 offset:58432
	v_cvt_pk_bf16_f32 v52, v233, v235
	v_cvt_pk_bf16_f32 v53, v236, v237
	v_cvt_pk_bf16_f32 v54, v60, v61
	v_cvt_pk_bf16_f32 v55, v62, v63
	s_waitcnt lgkmcnt(2)
	s_nop 0
	v_mfma_f32_32x32x16_bf16 v[16:31], v[48:51], v[52:55], v[16:31]
	v_add_f32_e32 v48, v235, v234
	v_add_f32_e32 v48, v236, v48
	v_add_f32_e32 v48, v237, v48
	v_add_f32_e32 v48, v60, v48
	v_add_f32_e32 v48, v61, v48
	v_add_f32_e32 v48, v62, v48
	v_add_f32_e32 v48, v63, v48
	s_waitcnt lgkmcnt(0)
	v_mfma_f32_32x32x16_bf16 v[0:15], v[56:59], v[52:55], v[0:15]
	v_add_f32_e32 v60, v238, v48
	s_branch .Lattn2_t4f

; #define LAS __attribute__((address_space(3)))
; __device__ __forceinline__ unsigned pk2(float lo, float hi) { f32x2_t v = {lo, hi}; bf16x2_t b = __builtin_convertvector(v, bf16x2_t); return __builtin_bit_cast(unsigned, b); }
; __device__ __forceinline__ s16x4 trrd(LAS const unsigned char* p) { return __builtin_bit_cast(s16x4, __builtin_amdgcn_ds_read_tr16_b64_v4i16((LAS v4i16_t*)p)); }
; template <bool FUSED> __device__ __forceinline__ void attn_phase(const Args& a, LAS unsigned char* lds, int tid, int lane, int wave) {
;     ...
;         for (int j = 0; j < 5; ++j) {
;             f32x16 st;
; #pragma unroll
;             for (int i = 0; i < 16; ++i) st[i] = -mb;
;             LAS const unsigned char* kp = lds + (32 * wave + 32 * j + l31) * KP + 16 * h;
; #pragma unroll
;             for (int ks = 0; ks < 4; ++ks) { const bf16x8 kf = *(LAS const bf16x8*)(kp + 32 * ks); st = __builtin_amdgcn_mfma_f32_32x32x16_bf16(kf, qf[ks], st, 0, 0, 0); }
;             sum += attn_tile_exp(st, j, tlf, bsl, rlo, rhi);
; #pragma unroll
;             for (int s2 = 0; s2 < 2; ++s2) { u32x4 pw; pw.x = pk2(st[8 * s2 + 0], st[8 * s2 + 1]); pw.y = pk2(st[8 * s2 + 2], st[8 * s2 + 3]); pw.z = pk2(st[8 * s2 + 4], st[8 * s2 + 5]); pw.w = pk2(st[8 * s2 + 6], st[8 * s2 + 7]);
;                 const bf16x8 pf = __builtin_bit_cast(bf16x8, pw);
;                 LAS const unsigned char* vp = lds + LDS_VOFF + (32 * wave + 32 * j + 16 * s2 + 4 * h + q) * VP + 32 * blk + 8 * p;
; #pragma unroll
;                 for (int dt = 0; dt < 2; ++dt) { const s16x4 lo = trrd(vp + dt * 64), hi = trrd(vp + 8 * VP + dt * 64);
;                     const bf16x8 vf = __builtin_shufflevector(lo, hi, 0, 1, 2, 3, 4, 5, 6, 7);
;                     o[dt] = __builtin_amdgcn_mfma_f32_32x32x16_bf16(vf, pf, o[dt], 0, 0, 0); } }
;             __builtin_amdgcn_sched_barrier(0);
;         }
.Lattn2_t4f:
	s_sub_i32 s99, s99, 32
	s_cmp_gt_i32 s98, s99
	s_cbranch_scc1 .Lattn2_skip4
	ds_read_b128 v[48:51], v214
	ds_read_b128 v[52:55], v214 offset:32
	s_waitcnt lgkmcnt(1)
	v_mfma_f32_32x32x16_bf16 v[32:47], v[48:51], v[96:99], v[32:47]
	ds_read_b128 v[48:51], v214 offset:64
	ds_read_b128 v[56:59], v214 offset:96
	s_waitcnt lgkmcnt(2)
	v_mfma_f32_32x32x16_bf16 v[32:47], v[52:55], v[100:103], v[32:47]
	s_waitcnt lgkmcnt(1)
	v_mfma_f32_32x32x16_bf16 v[32:47], v[48:51], v[104:107], v[32:47]
	s_waitcnt lgkmcnt(0)
	v_mfma_f32_32x32x16_bf16 v[32:47], v[56:59], v[108:111], v[32:47]
	s_nop 11
	v_fma_f32 v32, v170, |v244|, v32
	v_fma_f32 v33, v170, |v245|, v33
	v_fma_f32 v34, v170, |v246|, v34
	v_fma_f32 v35, v170, |v247|, v35
	v_fma_f32 v36, v170, |v248|, v36
	v_fma_f32 v37, v170, |v249|, v37
	v_exp_f32_e32 v49, v33
	v_mov_b32_e32 v33, v37
	v_exp_f32_e32 v53, v33
	v_exp_f32_e32 v50, v34
	v_fma_f32 v33, v170, |v250|, v38
	v_exp_f32_e32 v48, v32
	v_exp_f32_e32 v54, v33
	v_fma_f32 v33, v170, |v251|, v39
	v_exp_f32_e32 v51, v35
	v_exp_f32_e32 v52, v36
	v_add_f32_e32 v32, 0, v48
	v_exp_f32_e32 v39, v33
	v_add_f32_e32 v32, v49, v32
	v_add_f32_e32 v32, v50, v32
	v_fma_f32 v33, v170, |v252|, v40
	v_add_f32_e32 v32, v51, v32
	v_add_f32_e32 v32, v52, v32
	v_exp_f32_e32 v55, v33
	v_add_f32_e32 v32, v53, v32
	v_add_f32_e32 v32, v54, v32
	v_add_f32_e32 v32, v39, v32
	v_add_f32_e32 v56, v55, v32
	v_fma_f32 v32, v170, |v253|, v41
	v_exp_f32_e32 v57, v32
	v_fma_f32 v32, v170, |v254|, v42
	v_exp_f32_e32 v58, v32
	v_fma_f32 v32, v170, |v255|, v43
	v_exp_f32_e32 v59, v32
	v_fma_f32 v32, v170, |v164|, v44
	v_exp_f32_e32 v44, v32
	v_fma_f32 v32, v170, |v165|, v45
	v_exp_f32_e32 v45, v32
	v_fma_f32 v36, v170, |v166|, v46
	ds_read_b64_tr_b16 v[32:33], v215 offset:55296
	ds_read_b64_tr_b16 v[34:35], v215 offset:56832
	ds_read_b64_tr_b16 v[42:43], v215 offset:56896
	ds_read_b64_tr_b16 v[40:41], v215 offset:55360
	v_exp_f32_e32 v46, v36
	v_cvt_pk_bf16_f32 v36, v48, v49
	v_cvt_pk_bf16_f32 v37, v50, v51
	v_cvt_pk_bf16_f32 v38, v52, v53
	v_cvt_pk_bf16_f32 v39, v54, v39
	s_waitcnt lgkmcnt(2)
	s_nop 0
	v_mfma_f32_32x32x16_bf16 v[16:31], v[32:35], v[36:39], v[16:31]
	v_fma_f32 v47, v170, |v167|, v47
	ds_read_b64_tr_b16 v[32:33], v215 offset:58368
	ds_read_b64_tr_b16 v[34:35], v215 offset:59904
	v_exp_f32_e32 v47, v47
	s_waitcnt lgkmcnt(2)
	v_mfma_f32_32x32x16_bf16 v[0:15], v[40:43], v[36:39], v[0:15]
	ds_read_b64_tr_b16 v[42:43], v215 offset:59968
	ds_read_b64_tr_b16 v[40:41], v215 offset:58432
	v_cvt_pk_bf16_f32 v36, v55, v57
	v_cvt_pk_bf16_f32 v37, v58, v59
	v_cvt_pk_bf16_f32 v38, v44, v45
	v_cvt_pk_bf16_f32 v39, v46, v47
	s_waitcnt lgkmcnt(2)
	s_nop 0
	v_mfma_f32_32x32x16_bf16 v[16:31], v[32:35], v[36:39], v[16:31]
	v_add_f32_e32 v32, v57, v56
	v_add_f32_e32 v32, v58, v32
	v_add_f32_e32 v32, v59, v32
	v_add_f32_e32 v32, v44, v32
	v_add_f32_e32 v32, v45, v32
	v_add_f32_e32 v32, v46, v32
	v_add_f32_e32 v32, v47, v32
	s_waitcnt lgkmcnt(0)
	v_mfma_f32_32x32x16_bf16 v[0:15], v[40:43], v[36:39], v[0:15]
	v_add_f32_e32 v236, v60, v32
	s_branch .Lattn2_end
.Lattn2_skip4:
	v_mov_b32_e32 v236, v60
